# third norm_rows loop: second row x loads issued at loop top together with the first row, counted waits rederived
# speedup vs baseline: 1.0036x; 1.0014x over previous
; __device__ __forceinline__ unsigned pk2(float lo, float hi) { return pg8::pk_bf16_rne(lo, hi); }
; __device__ __forceinline__ float wave_sum(float v) { v = row16_allsum(v); v = rows_pair_sum(v); v = halves_pair_sum(v); return v; }
; __device__ __forceinline__ void norm_rows(const Params& P, const float* src, float* copy_dst, int l, int shi, int gw, int NGW, int lane) {
;     ...
;     for (int m0 = 2 * gw; m0 < T; m0 += 2 * NGW) {
;         f32x4 v[2][4]; float s[2] = {0.f, 0.f};
; #pragma unroll
;         for (int q = 0; q < 2; ++q) { const f32x4* xr = (const f32x4*)(src + (size_t)(m0 + q) * D) + lane;
; #pragma unroll
;             for (int j = 0; j < 4; ++j) v[q][j] = xr[64 * j]; }
; #pragma unroll
;         for (int q = 0; q < 2; ++q) {
; #pragma unroll
;             for (int j = 0; j < 4; ++j) s[q] += (v[q][j].x * v[q][j].x + v[q][j].y * v[q][j].y) + (v[q][j].z * v[q][j].z + v[q][j].w * v[q][j].w); }
; #pragma unroll
;         for (int q = 0; q < 2; ++q) {
;             const int m = m0 + q, b = m >> 12;
;             const float rstd = 1.0f / sqrtf(wave_sum(s[q]) * (1.0f / D) + 1e-6f);
;             const f32x4* sh = (const f32x4*)(modl + (size_t)b * 9216 + shi * 1024) + lane;
;             const f32x4* sc = (const f32x4*)(modl + (size_t)b * 9216 + (shi + 1) * 1024) + lane;
;             u32x2* o8 = (u32x2*)(H + (size_t)m * D) + lane;
; #pragma unroll
;             for (int j = 0; j < 4; ++j) { const f32x4 a = sh[64 * j], c = sc[64 * j]; const f32x4 o = v[q][j] * rstd * (c + 1.0f) + a;
;                 u32x2 w; w.x = pk2(o.x, o.y); w.y = pk2(o.z, o.w); o8[64 * j] = w; }
;             if (copy_dst) { f32x4* cd = (f32x4*)(copy_dst + (size_t)m * D) + lane;
; #pragma unroll
;                 for (int j = 0; j < 4; ++j) cd[64 * j] = v[q][j]; }
.LBB0_1048:
	v_ashrrev_i32_e32 v100, 12, v32
	v_mul_hi_i32_i24_e32 v101, 0x9000, v100
	v_mul_i32_i24_e32 v100, 0x9000, v100
	v_lshl_add_u64 v[100:101], s[12:13], 0, v[100:101]
	v_lshl_add_u64 v[102:103], v[100:101], 0, v[152:153]
	v_lshl_add_u64 v[104:105], v[102:103], 0, s[24:25]
	global_load_dwordx4 v[60:63], v[102:103], off
	global_load_dwordx4 v[64:67], v[102:103], off offset:1024
	global_load_dwordx4 v[68:71], v[102:103], off offset:2048
	global_load_dwordx4 v[72:75], v[102:103], off offset:3072
	global_load_dwordx4 v[76:79], v[104:105], off
	global_load_dwordx4 v[80:83], v[104:105], off offset:1024
	global_load_dwordx4 v[84:87], v[104:105], off offset:2048
	global_load_dwordx4 v[88:91], v[104:105], off offset:3072
	v_lshl_add_u64 v[0:1], v[40:41], 0, v[34:35]
	global_load_dwordx4 v[16:19], v[0:1], off
	global_load_dwordx4 v[20:23], v[0:1], off offset:1024
	global_load_dwordx4 v[24:27], v[0:1], off offset:2048
	global_load_dwordx4 v[28:31], v[0:1], off offset:3072
	v_lshl_add_u64 v[122:123], v[0:1], 0, s[24:25]
	global_load_dwordx4 v[106:109], v[122:123], off
	global_load_dwordx4 v[110:113], v[122:123], off offset:1024
	global_load_dwordx4 v[114:117], v[122:123], off offset:2048
	global_load_dwordx4 v[118:121], v[122:123], off offset:3072
	v_ashrrev_i32_e32 v2, 12, v32
	v_mul_hi_i32_i24_e32 v3, 0x9000, v2
	v_mul_i32_i24_e32 v2, 0x9000, v2
	v_lshl_add_u64 v[2:3], s[12:13], 0, v[2:3]
	v_lshl_add_u64 v[42:43], v[2:3], 0, v[152:153]
	v_add_co_u32_e32 v2, vcc, s36, v42
	s_waitcnt vmcnt(7)
	v_mul_f32_e32 v8, v17, v17
	v_addc_co_u32_e32 v3, vcc, 0, v43, vcc
	global_load_dwordx4 v[46:49], v[2:3], off
	global_load_dwordx4 v[50:53], v[42:43], off
	v_mul_f32_e32 v9, v19, v19
	s_waitcnt vmcnt(8)
	v_mul_f32_e32 v10, v21, v21
	v_mul_f32_e32 v11, v23, v23
	s_waitcnt vmcnt(7)
	v_mul_f32_e32 v14, v25, v25
	v_mul_f32_e32 v15, v27, v27
	v_fmac_f32_e32 v8, v16, v16
	v_fmac_f32_e32 v9, v18, v18
	v_fmac_f32_e32 v10, v20, v20
	v_fmac_f32_e32 v11, v22, v22
	s_waitcnt vmcnt(6)
	v_mul_f32_e32 v33, v29, v29
	v_mul_f32_e32 v44, v31, v31
	v_fmac_f32_e32 v14, v24, v24
	v_fmac_f32_e32 v15, v26, v26
	v_add_f32_e32 v8, v8, v9
	v_add_f32_e32 v9, v10, v11
	v_fmac_f32_e32 v33, v28, v28
	v_fmac_f32_e32 v44, v30, v30
	v_add_f32_e32 v10, v14, v15
	v_add_f32_e32 v8, v8, v9
	v_add_f32_e32 v11, v33, v44
	v_add_f32_e32 v8, v8, v10
	v_add_f32_e32 v8, v8, v11
	v_add_co_u32_e32 v12, vcc, 0x1000, v0
	s_nop 0
	v_add_f32_dpp v8, v8, v8 row_ror:8 row_mask:0xf bank_mask:0xf bound_ctrl:1
	v_addc_co_u32_e32 v13, vcc, 0, v1, vcc
	s_nop 0
	v_add_f32_dpp v8, v8, v8 row_ror:4 row_mask:0xf bank_mask:0xf bound_ctrl:1
	s_nop 1
	v_add_f32_dpp v8, v8, v8 row_ror:2 row_mask:0xf bank_mask:0xf bound_ctrl:1
	v_lshl_add_u64 v[44:45], v[42:43], 0, s[24:25]
	s_waitcnt vmcnt(1)
	v_pk_add_f32 v[48:49], v[48:49], 1.0 op_sel_hi:[1,0]
	v_add_f32_dpp v8, v8, v8 row_ror:1 row_mask:0xf bank_mask:0xf bound_ctrl:1
	v_mov_b32_e32 v9, v8
	s_nop 1
	v_permlane16_swap_b32_e32 v8, v9
	v_add_f32_e32 v8, v8, v9
	v_mov_b32_e32 v9, v8
	s_nop 1
	v_permlane32_swap_b32_e32 v8, v9
	v_add_f32_e32 v8, v8, v9
	v_fmamk_f32 v8, v8, 0x3a800000, v155
	v_mul_f32_e32 v9, 0x4f800000, v8
	v_cmp_gt_f32_e32 vcc, s43, v8
	v_pk_add_f32 v[46:47], v[46:47], 1.0 op_sel_hi:[1,0]
	s_nop 0
	v_cndmask_b32_e32 v33, v8, v9, vcc
	v_sqrt_f32_e32 v54, v33
	s_nop 0
	v_add_u32_e32 v55, -1, v54
	v_add_u32_e32 v56, 1, v54
	v_fma_f32 v57, -v55, v54, v33
	v_fma_f32 v58, -v56, v54, v33
	v_cmp_ge_f32_e64 s[4:5], 0, v57
	s_nop 1
	v_cndmask_b32_e64 v54, v54, v55, s[4:5]
	v_cmp_lt_f32_e64 s[4:5], 0, v58
	s_nop 1
	v_cndmask_b32_e64 v54, v54, v56, s[4:5]
	v_mul_f32_e32 v55, 0x37800000, v54
	v_cndmask_b32_e32 v54, v54, v55, vcc
	v_cmp_class_f32_e32 vcc, v33, v175
	s_nop 1
	v_cndmask_b32_e32 v33, v54, v33, vcc
	v_div_scale_f32 v54, s[4:5], v33, v33, 1.0
	v_rcp_f32_e32 v55, v54
	v_div_scale_f32 v56, vcc, 1.0, v33, 1.0
	v_fma_f32 v57, -v54, v55, 1.0
	v_fmac_f32_e32 v55, v57, v55
	v_mul_f32_e32 v57, v56, v55
	v_fma_f32 v58, -v54, v57, v56
	v_fmac_f32_e32 v57, v58, v55
	v_fma_f32 v54, -v54, v57, v56
	v_div_fmas_f32 v54, v54, v55, v57
	v_div_fixup_f32 v54, v54, v33, 1.0
	v_pk_mul_f32 v[56:57], v[16:17], v[54:55] op_sel_hi:[1,0]
	v_pk_mul_f32 v[58:59], v[18:19], v[54:55] op_sel_hi:[1,0]
	s_waitcnt vmcnt(0)
	v_pk_fma_f32 v[46:47], v[46:47], v[56:57], v[50:51]
	v_pk_fma_f32 v[48:49], v[48:49], v[58:59], v[52:53]
	v_cvt_pk_bf16_f32 v46, v46, v47
	v_cvt_pk_bf16_f32 v47, v48, v49
	global_store_dwordx2 v[38:39], v[46:47], off offset:-3584
	s_nop 1
	v_mov_b64_e32 v[46:47], v[80:81]
	v_mov_b64_e32 v[48:49], v[82:83]
	s_nop 0
	v_mov_b64_e32 v[50:51], v[64:65]
	v_mov_b64_e32 v[52:53], v[66:67]
	v_pk_mul_f32 v[56:57], v[20:21], v[54:55] op_sel_hi:[1,0]
	v_pk_mul_f32 v[58:59], v[22:23], v[54:55] op_sel_hi:[1,0]
	v_cndmask_b32_e64 v33, 0, 1, s[14:15]
	v_cmp_ne_u32_e64 s[4:5], 1, v33
	s_andn2_b64 vcc, exec, s[14:15]
	v_pk_add_f32 v[48:49], v[48:49], 1.0 op_sel_hi:[1,0]
	v_pk_add_f32 v[46:47], v[46:47], 1.0 op_sel_hi:[1,0]
	v_pk_fma_f32 v[48:49], v[48:49], v[58:59], v[52:53]
	v_pk_fma_f32 v[46:47], v[46:47], v[56:57], v[50:51]
	v_pk_mul_f32 v[56:57], v[24:25], v[54:55] op_sel_hi:[1,0]
	v_cvt_pk_bf16_f32 v46, v46, v47
	v_cvt_pk_bf16_f32 v47, v48, v49
	global_store_dwordx2 v[38:39], v[46:47], off offset:-3072
	s_nop 1
	v_mov_b64_e32 v[46:47], v[84:85]
	v_mov_b64_e32 v[48:49], v[86:87]
	s_nop 0
	v_mov_b64_e32 v[50:51], v[68:69]
	v_mov_b64_e32 v[52:53], v[70:71]
	v_pk_mul_f32 v[58:59], v[26:27], v[54:55] op_sel_hi:[1,0]
	v_pk_add_f32 v[48:49], v[48:49], 1.0 op_sel_hi:[1,0]
	v_pk_add_f32 v[46:47], v[46:47], 1.0 op_sel_hi:[1,0]
	v_pk_fma_f32 v[48:49], v[48:49], v[58:59], v[52:53]
	v_pk_fma_f32 v[46:47], v[46:47], v[56:57], v[50:51]
	v_pk_mul_f32 v[56:57], v[28:29], v[54:55] op_sel_hi:[1,0]
	v_cvt_pk_bf16_f32 v46, v46, v47
	v_cvt_pk_bf16_f32 v47, v48, v49
	global_store_dwordx2 v[38:39], v[46:47], off offset:-2560
	s_nop 1
	v_mov_b64_e32 v[46:47], v[88:89]
	v_mov_b64_e32 v[48:49], v[90:91]
	s_nop 0
	v_mov_b64_e32 v[50:51], v[72:73]
	v_mov_b64_e32 v[52:53], v[74:75]
	v_pk_mul_f32 v[54:55], v[30:31], v[54:55] op_sel_hi:[1,0]
	v_pk_add_f32 v[48:49], v[48:49], 1.0 op_sel_hi:[1,0]
	v_pk_add_f32 v[46:47], v[46:47], 1.0 op_sel_hi:[1,0]
	v_pk_fma_f32 v[48:49], v[54:55], v[48:49], v[52:53]
	v_pk_fma_f32 v[46:47], v[56:57], v[46:47], v[50:51]
	s_nop 0
	v_cvt_pk_bf16_f32 v46, v46, v47
	v_cvt_pk_bf16_f32 v47, v48, v49
	global_store_dwordx2 v[38:39], v[46:47], off offset:-2048
	v_lshl_add_u64 v[46:47], v[36:37], 0, v[34:35]
	s_cbranch_vccnz .LBB0_1050
	global_store_dwordx4 v[46:47], v[16:19], off
	global_store_dwordx4 v[46:47], v[20:23], off offset:1024
	global_store_dwordx4 v[46:47], v[24:27], off offset:2048
	global_store_dwordx4 v[46:47], v[28:31], off offset:3072
; __device__ __forceinline__ unsigned pk2(float lo, float hi) { return pg8::pk_bf16_rne(lo, hi); }
; __device__ __forceinline__ float wave_sum(float v) { v = row16_allsum(v); v = rows_pair_sum(v); v = halves_pair_sum(v); return v; }
; __device__ __forceinline__ void norm_rows(const Params& P, const float* src, float* copy_dst, int l, int shi, int gw, int NGW, int lane) {
;     ...
;         for (int q = 0; q < 2; ++q) {
; #pragma unroll
;             for (int j = 0; j < 4; ++j) s[q] += (v[q][j].x * v[q][j].x + v[q][j].y * v[q][j].y) + (v[q][j].z * v[q][j].z + v[q][j].w * v[q][j].w); }
; #pragma unroll
;         for (int q = 0; q < 2; ++q) {
;             const int m = m0 + q, b = m >> 12;
;             const float rstd = 1.0f / sqrtf(wave_sum(s[q]) * (1.0f / D) + 1e-6f);
;             const f32x4* sh = (const f32x4*)(modl + (size_t)b * 9216 + shi * 1024) + lane;
;             const f32x4* sc = (const f32x4*)(modl + (size_t)b * 9216 + (shi + 1) * 1024) + lane;
;             u32x2* o8 = (u32x2*)(H + (size_t)m * D) + lane;
; #pragma unroll
;             for (int j = 0; j < 4; ++j) { const f32x4 a = sh[64 * j], c = sc[64 * j]; const f32x4 o = v[q][j] * rstd * (c + 1.0f) + a;
;                 u32x2 w; w.x = pk2(o.x, o.y); w.y = pk2(o.z, o.w); o8[64 * j] = w; }
;             if (copy_dst) { f32x4* cd = (f32x4*)(copy_dst + (size_t)m * D) + lane;
; #pragma unroll
;                 for (int j = 0; j < 4; ++j) cd[64 * j] = v[q][j]; }
.LBB0_1050:
	s_nop 1
	v_mov_b64_e32 v[0:1], v[106:107]
	v_mov_b64_e32 v[2:3], v[108:109]
	v_mov_b64_e32 v[4:5], v[110:111]
	v_mov_b64_e32 v[6:7], v[112:113]
	v_mov_b64_e32 v[8:9], v[114:115]
	v_mov_b64_e32 v[10:11], v[116:117]
	v_mov_b64_e32 v[12:13], v[118:119]
	v_mov_b64_e32 v[14:15], v[120:121]
	v_mov_b64_e32 v[16:17], v[76:77]
	v_mov_b64_e32 v[18:19], v[78:79]
	s_nop 0
	v_mov_b64_e32 v[20:21], v[60:61]
	v_mov_b64_e32 v[22:23], v[62:63]
	v_mul_f32_e32 v24, v1, v1
	v_mul_f32_e32 v25, v3, v3
	v_mul_f32_e32 v26, v5, v5
	v_mul_f32_e32 v27, v7, v7
	v_mul_f32_e32 v28, v9, v9
	v_mul_f32_e32 v29, v11, v11
	v_fmac_f32_e32 v24, v0, v0
	v_fmac_f32_e32 v25, v2, v2
	v_fmac_f32_e32 v26, v4, v4
	v_fmac_f32_e32 v27, v6, v6
	v_mul_f32_e32 v30, v13, v13
	v_mul_f32_e32 v31, v15, v15
	v_fmac_f32_e32 v28, v8, v8
	v_fmac_f32_e32 v29, v10, v10
	v_add_f32_e32 v24, v24, v25
	v_add_f32_e32 v25, v26, v27
	v_fmac_f32_e32 v30, v12, v12
	v_fmac_f32_e32 v31, v14, v14
	v_add_f32_e32 v26, v28, v29
	v_add_f32_e32 v24, v24, v25
	v_add_f32_e32 v27, v30, v31
	v_add_f32_e32 v24, v24, v26
	v_add_f32_e32 v24, v24, v27
	v_pk_add_f32 v[18:19], v[18:19], 1.0 op_sel_hi:[1,0]
	v_add_f32_dpp v24, v24, v24 row_ror:8 row_mask:0xf bank_mask:0xf bound_ctrl:1
	v_pk_add_f32 v[16:17], v[16:17], 1.0 op_sel_hi:[1,0]
	s_nop 0
	v_add_f32_dpp v24, v24, v24 row_ror:4 row_mask:0xf bank_mask:0xf bound_ctrl:1
	s_nop 1
	v_add_f32_dpp v24, v24, v24 row_ror:2 row_mask:0xf bank_mask:0xf bound_ctrl:1
	s_nop 1
	v_add_f32_dpp v24, v24, v24 row_ror:1 row_mask:0xf bank_mask:0xf bound_ctrl:1
	v_mov_b32_e32 v25, v24
	s_nop 1
	v_permlane16_swap_b32_e32 v24, v25
	v_add_f32_e32 v24, v24, v25
	v_mov_b32_e32 v25, v24
	s_nop 1
	v_permlane32_swap_b32_e32 v24, v25
	v_add_f32_e32 v24, v24, v25
	v_fmamk_f32 v24, v24, 0x3a800000, v155
	v_mul_f32_e32 v25, 0x4f800000, v24
	v_cmp_gt_f32_e32 vcc, s43, v24
	s_nop 1
	v_cndmask_b32_e32 v24, v24, v25, vcc
	v_sqrt_f32_e32 v25, v24
	s_nop 0
	v_add_u32_e32 v26, -1, v25
	v_add_u32_e32 v27, 1, v25
	v_fma_f32 v28, -v26, v25, v24
	v_fma_f32 v29, -v27, v25, v24
	v_cmp_ge_f32_e64 s[6:7], 0, v28
	s_nop 1
	v_cndmask_b32_e64 v25, v25, v26, s[6:7]
	v_cmp_lt_f32_e64 s[6:7], 0, v29
	s_nop 1
	v_cndmask_b32_e64 v25, v25, v27, s[6:7]
	v_mul_f32_e32 v26, 0x37800000, v25
	v_cndmask_b32_e32 v25, v25, v26, vcc
	v_cmp_class_f32_e32 vcc, v24, v175
	s_nop 1
	v_cndmask_b32_e32 v24, v25, v24, vcc
	v_div_scale_f32 v25, s[6:7], v24, v24, 1.0
	v_rcp_f32_e32 v26, v25
	v_div_scale_f32 v27, vcc, 1.0, v24, 1.0
	v_fma_f32 v28, -v25, v26, 1.0
	v_fmac_f32_e32 v26, v28, v26
	v_mul_f32_e32 v28, v27, v26
	v_fma_f32 v29, -v25, v28, v27
	v_fmac_f32_e32 v28, v29, v26
	v_fma_f32 v25, -v25, v28, v27
	v_div_fmas_f32 v25, v25, v26, v28
	v_div_fixup_f32 v24, v25, v24, 1.0
	v_pk_mul_f32 v[26:27], v[0:1], v[24:25] op_sel_hi:[1,0]
	v_pk_mul_f32 v[28:29], v[2:3], v[24:25] op_sel_hi:[1,0]
	v_pk_fma_f32 v[16:17], v[16:17], v[26:27], v[20:21]
	v_pk_fma_f32 v[18:19], v[18:19], v[28:29], v[22:23]
	v_cvt_pk_bf16_f32 v16, v16, v17
	v_cvt_pk_bf16_f32 v17, v18, v19
	global_store_dwordx2 v[38:39], v[16:17], off offset:-1536
	s_nop 1
	v_mov_b64_e32 v[16:17], v[80:81]
	v_mov_b64_e32 v[18:19], v[82:83]
	s_nop 0
	v_mov_b64_e32 v[20:21], v[64:65]
	v_mov_b64_e32 v[22:23], v[66:67]
	v_pk_mul_f32 v[26:27], v[4:5], v[24:25] op_sel_hi:[1,0]
	v_pk_mul_f32 v[28:29], v[6:7], v[24:25] op_sel_hi:[1,0]
	s_and_b64 vcc, exec, s[4:5]
	v_pk_add_f32 v[18:19], v[18:19], 1.0 op_sel_hi:[1,0]
	v_pk_add_f32 v[16:17], v[16:17], 1.0 op_sel_hi:[1,0]
	v_pk_fma_f32 v[18:19], v[18:19], v[28:29], v[22:23]
	v_pk_fma_f32 v[16:17], v[16:17], v[26:27], v[20:21]
	v_pk_mul_f32 v[26:27], v[8:9], v[24:25] op_sel_hi:[1,0]
	v_cvt_pk_bf16_f32 v16, v16, v17
	v_cvt_pk_bf16_f32 v17, v18, v19
	global_store_dwordx2 v[38:39], v[16:17], off offset:-1024
	s_nop 1
	v_mov_b64_e32 v[16:17], v[84:85]
	v_mov_b64_e32 v[18:19], v[86:87]
	s_nop 0
	v_mov_b64_e32 v[20:21], v[68:69]
	v_mov_b64_e32 v[22:23], v[70:71]
	v_pk_mul_f32 v[28:29], v[10:11], v[24:25] op_sel_hi:[1,0]
	v_pk_add_f32 v[18:19], v[18:19], 1.0 op_sel_hi:[1,0]
	v_pk_add_f32 v[16:17], v[16:17], 1.0 op_sel_hi:[1,0]
	v_pk_fma_f32 v[18:19], v[18:19], v[28:29], v[22:23]
	v_pk_fma_f32 v[16:17], v[16:17], v[26:27], v[20:21]
	v_pk_mul_f32 v[26:27], v[12:13], v[24:25] op_sel_hi:[1,0]
	v_cvt_pk_bf16_f32 v16, v16, v17
	v_cvt_pk_bf16_f32 v17, v18, v19
	global_store_dwordx2 v[38:39], v[16:17], off offset:-512
	s_nop 1
	v_mov_b64_e32 v[16:17], v[88:89]
	v_mov_b64_e32 v[18:19], v[90:91]
	s_nop 0
	v_mov_b64_e32 v[20:21], v[72:73]
	v_mov_b64_e32 v[22:23], v[74:75]
	v_pk_mul_f32 v[24:25], v[14:15], v[24:25] op_sel_hi:[1,0]
	v_pk_add_f32 v[18:19], v[18:19], 1.0 op_sel_hi:[1,0]
	v_pk_add_f32 v[16:17], v[16:17], 1.0 op_sel_hi:[1,0]
	v_pk_fma_f32 v[18:19], v[24:25], v[18:19], v[22:23]
	v_pk_fma_f32 v[16:17], v[26:27], v[16:17], v[20:21]
	s_nop 0
	v_cvt_pk_bf16_f32 v16, v16, v17
	v_cvt_pk_bf16_f32 v17, v18, v19
	global_store_dwordx2 v[38:39], v[16:17], off
	s_cbranch_vccnz .LBB0_1047
	v_add_co_u32_e32 v16, vcc, 0x1000, v46
	s_nop 1
	v_addc_co_u32_e32 v17, vcc, 0, v47, vcc
	global_store_dwordx4 v[16:17], v[0:3], off
	global_store_dwordx4 v[16:17], v[4:7], off offset:1024
	global_store_dwordx4 v[16:17], v[8:11], off offset:2048
	global_store_dwordx4 v[16:17], v[12:15], off offset:3072
	s_branch .LBB0_1047
